# grid barrier: per-XCD generation add (no longer polled by anyone) and its wait removed from the XCD leader's exit path
# baseline (speedup 1.0000x reference)
.LBB0_201:
	s_or_b64 exec, exec, s[6:7]
	s_mov_b64 s[6:7], exec
	v_mbcnt_lo_u32_b32 v0, s6, 0
	v_mbcnt_hi_u32_b32 v0, s7, v0
	v_cmp_eq_u32_e32 vcc, 0, v0
	s_waitcnt vmcnt(0)
	buffer_inv sc1
	s_and_saveexec_b64 s[8:9], vcc
	s_cbranch_execz .LBB0_203
	s_bcnt1_i32_b64 s0, s[6:7]
	v_mov_b32_e32 v0, s0
	v_readlane_b32 s0, v254, 31
	v_readlane_b32 s1, v254, 32
	s_nop 4
	s_nop 0

.LBB0_1567:
	s_bcnt1_i32_b64 s0, s[6:7]
	v_mov_b32_e32 v0, s0
	v_readlane_b32 s0, v254, 31
	v_readlane_b32 s1, v254, 32
	s_nop 4
	s_nop 0
	s_getpc_b64 s[98:99]
